# speedup vs baseline: 1.0067x; 1.0067x over previous
; DEVINL float bf2f(u16 h) { return __uint_as_float(((unsigned)h) << 16); }
; DEVINL void ret_out_phase(CParams& p, const Ctx& cx, int l, const GI& gi) {
;     ...
;     const float* gn = p.gn_gain + (size_t)l * DM + h * 256 + fr * 16;
;     float gv[16];
; #pragma unroll
;     for (int q4 = 0; q4 < 4; ++q4) { const float4 g4 = *(const float4*)(gn + q4 * 4); gv[q4 * 4] = g4.x; gv[q4 * 4 + 1] = g4.y; gv[q4 * 4 + 2] = g4.z; gv[q4 * 4 + 3] = g4.w; }
; #pragma unroll
;     for (int j = 0; j < 4; ++j) {
;       float sm = 0.f;
; #pragma unroll
;       for (int et = 0; et < 16; ++et) sm += o[et][j];
; #pragma unroll
;       for (int x = 1; x < 16; x <<= 1) sm += shflx(sm, x, lane);
;       const float mu = sm * (1.f / 256.f);
;       float vs = 0.f;
; #pragma unroll
;       for (int et = 0; et < 16; ++et) { const float d = o[et][j] - mu; vs += d * d; }
; #pragma unroll
;       for (int x = 1; x < 16; x <<= 1) vs += shflx(vs, x, lane);
;       const float rsd = rsqrtf(vs * (1.f / 256.f) + 1e-5f);
;       const size_t ro = (size_t)(row0 + wave * 16 + fq * 4 + j) * DM + h * 256 + fr * 16;
;       const bf16x8 s0 = *(const bf16x8*)(p.sg + ro), s1 = *(const bf16x8*)(p.sg + ro + 8);
;       bf16x8 y0, y1;
; #pragma unroll
;       for (int et = 0; et < 8; ++et) {
;         y0[et] = (short)f2bf(bf2f((u16)s0[et]) * ((o[et][j] - mu) * rsd * gv[et]));
;         y1[et] = (short)f2bf(bf2f((u16)s1[et]) * ((o[et + 8][j] - mu) * rsd * gv[et + 8]));
;       }
;       *(bf16x8*)(p.y + ro) = y0; *(bf16x8*)(p.y + ro + 8) = y1;
;     }
.LBB0_268:
	v_add_u32_e32 v0, s28, v99
	s_waitcnt vmcnt(2)
	v_or_b32_e32 v22, v0, v137
	v_ashrrev_i32_e32 v23, 31, v22
	v_lshlrev_b64 v[2:3], 10, v[22:23]
	v_or3_b32 v2, v2, v98, s96
	v_lshlrev_b64 v[24:25], 1, v[2:3]
	s_waitcnt vmcnt(1)
	v_lshl_add_u64 v[26:27], s[6:7], 0, v[24:25]
	v_mov_b32_e32 v170, v26
	v_mov_b32_e32 v171, v27
	global_load_dwordx4 v[18:21], v[26:27], off offset:16
	v_add_f32_e32 v0, 0, v94
	v_lshlrev_b32_e32 v2, 2, v134
	v_add_f32_e32 v3, 0, v95
	v_add_f32_e32 v4, v0, v90
	v_bfrev_b32_e32 v0, 0.5
	v_mov_b32_e32 v104, v94
	v_bitop3_b32 v99, v2, 4, v0 bitop3:0x6c
	v_bitop3_b32 v94, v2, 8, v0 bitop3:0x6c
	v_bitop3_b32 v23, v2, 16, v0 bitop3:0x6c
	v_bitop3_b32 v0, v2, 32, v0 bitop3:0x6c
	v_add_f32_e32 v2, v3, v91
	v_add_f32_e32 v3, v4, v86
	v_add_f32_e32 v11, v3, v78
	v_add_f32_e32 v11, v11, v70
	v_add_f32_e32 v11, v11, v62
	v_add_f32_e32 v11, v11, v54
	v_add_f32_e32 v11, v11, v46
	v_add_f32_e32 v11, v11, v82
	v_add_f32_e32 v11, v11, v74
	v_add_f32_e32 v11, v11, v66
	v_add_f32_e32 v11, v11, v58
	v_add_f32_e32 v11, v11, v50
	v_add_f32_e32 v11, v11, v42
	v_add_f32_e32 v11, v11, v38
	v_add_f32_e32 v11, v11, v34
	ds_bpermute_b32 v12, v99, v11
	v_add_f32_e32 v10, v2, v87
	v_add_f32_e32 v10, v10, v79
	v_add_f32_e32 v10, v10, v71
	v_add_f32_e32 v10, v10, v63
	s_waitcnt lgkmcnt(0)
	v_add_f32_e32 v11, v11, v12
	ds_bpermute_b32 v12, v94, v11
	v_add_f32_e32 v10, v10, v55
	v_add_f32_e32 v10, v10, v47
	v_add_f32_e32 v10, v10, v83
	v_add_f32_e32 v10, v10, v75
	s_waitcnt lgkmcnt(0)
	v_add_f32_e32 v11, v11, v12
	v_add_f32_e32 v10, v10, v67
	ds_bpermute_b32 v12, v23, v11
	v_add_f32_e32 v10, v10, v59
	s_lshl_b32 s16, s27, 10
	v_add_f32_e32 v10, v10, v51
	s_add_u32 s16, s24, s16
	v_add_f32_e32 v10, v10, v43
	v_lshlrev_b32_e32 v14, 2, v98
	s_addc_u32 s17, s25, 0
	v_add_f32_e32 v10, v10, v39
	v_mov_b32_e32 v101, v42
	v_mov_b32_e32 v103, v34
	global_load_dwordx4 v[2:5], v14, s[16:17] offset:48
	global_load_dwordx4 v[6:9], v14, s[16:17] offset:32
	v_add_f32_e32 v34, v10, v35
	s_waitcnt lgkmcnt(0)
	v_add_f32_e32 v42, v11, v12
	global_load_dwordx4 v[10:13], v14, s[16:17] offset:16
	s_nop 0
	global_load_dwordx4 v[14:17], v14, s[16:17]
	s_nop 0
	global_load_dwordx4 v[26:29], v[26:27], off
	v_mov_b32_e32 v102, v38
	ds_bpermute_b32 v38, v99, v34
	s_waitcnt vmcnt(6)
	v_mov_b32_e32 v33, v58
	v_mov_b32_e32 v100, v50
	ds_bpermute_b32 v50, v0, v42
	v_mov_b32_e32 v105, v90
	s_waitcnt lgkmcnt(1)
	v_add_f32_e32 v38, v34, v38
	ds_bpermute_b32 v58, v94, v38
	v_mov_b32_e32 v90, v95
	s_waitcnt lgkmcnt(1)
	v_add_f32_e32 v34, v42, v50
	v_mul_f32_e32 v34, 0x3b800000, v34
	v_mov_b32_e32 v30, v82
	s_waitcnt lgkmcnt(0)
	v_add_f32_e32 v38, v38, v58
	ds_bpermute_b32 v42, v23, v38
	v_mov_b32_e32 v31, v74
	v_pk_add_f32 v[104:105], v[104:105], v[34:35] op_sel_hi:[1,0] neg_lo:[0,1] neg_hi:[0,1]
	v_mov_b32_e32 v74, v83
	v_mov_b32_e32 v32, v66
	s_waitcnt lgkmcnt(0)
	v_add_f32_e32 v38, v38, v42
	ds_bpermute_b32 v42, v0, v38
	v_pk_add_f32 v[30:31], v[30:31], v[34:35] op_sel_hi:[1,0] neg_lo:[0,1] neg_hi:[0,1]
	v_pk_add_f32 v[32:33], v[32:33], v[34:35] op_sel_hi:[1,0] neg_lo:[0,1] neg_hi:[0,1]
	v_pk_add_f32 v[100:101], v[100:101], v[34:35] op_sel_hi:[1,0] neg_lo:[0,1] neg_hi:[0,1]
	v_pk_add_f32 v[102:103], v[102:103], v[34:35] op_sel_hi:[1,0] neg_lo:[0,1] neg_hi:[0,1]
	v_mov_b32_e32 v58, v67
	v_pk_mul_f32 v[106:107], v[32:33], v[32:33]
	s_waitcnt vmcnt(5)
	s_mov_b32 s100, 0x1000
	s_mov_b32 s101, 0
	v_lshl_add_u64 v[168:169], v[170:171], 0, s[100:101]
	global_load_dwordx4 v[172:175], v[170:171], off offset:2064
	global_load_dwordx4 v[176:179], v[170:171], off offset:2048
	global_load_dwordx4 v[180:183], v[168:169], off offset:16
	global_load_dwordx4 v[184:187], v[168:169], off
	global_load_dwordx4 v[188:191], v[168:169], off offset:2064
	global_load_dwordx4 v[192:195], v[168:169], off offset:2048
	v_and_b32_e32 v113, 0xffff0000, v18
	v_lshlrev_b32_e32 v112, 16, v18
	v_and_b32_e32 v115, 0xffff0000, v19
	v_lshlrev_b32_e32 v114, 16, v19
	v_mov_b32_e32 v18, v86
	v_mov_b32_e32 v19, v78
	v_pk_add_f32 v[116:117], v[18:19], v[34:35] op_sel_hi:[1,0] neg_lo:[0,1] neg_hi:[0,1]
	v_mov_b32_e32 v18, v70
	v_mov_b32_e32 v19, v62
	v_pk_add_f32 v[118:119], v[18:19], v[34:35] op_sel_hi:[1,0] neg_lo:[0,1] neg_hi:[0,1]
	v_mov_b32_e32 v18, v54
	v_mov_b32_e32 v19, v46
	v_pk_add_f32 v[120:121], v[18:19], v[34:35] op_sel_hi:[1,0] neg_lo:[0,1] neg_hi:[0,1]
	s_waitcnt lgkmcnt(0)
; DEVINL float bf2f(u16 h) { return __uint_as_float(((unsigned)h) << 16); }
; DEVINL void ret_out_phase(CParams& p, const Ctx& cx, int l, const GI& gi) {
;     ...
; #pragma unroll
;     for (int j = 0; j < 4; ++j) {
;       float sm = 0.f;
; #pragma unroll
;       for (int et = 0; et < 16; ++et) sm += o[et][j];
; #pragma unroll
;       for (int x = 1; x < 16; x <<= 1) sm += shflx(sm, x, lane);
;       const float mu = sm * (1.f / 256.f);
;       float vs = 0.f;
; #pragma unroll
;       for (int et = 0; et < 16; ++et) { const float d = o[et][j] - mu; vs += d * d; }
; #pragma unroll
;       for (int x = 1; x < 16; x <<= 1) vs += shflx(vs, x, lane);
;       const float rsd = rsqrtf(vs * (1.f / 256.f) + 1e-5f);
;       const size_t ro = (size_t)(row0 + wave * 16 + fq * 4 + j) * DM + h * 256 + fr * 16;
;       const bf16x8 s0 = *(const bf16x8*)(p.sg + ro), s1 = *(const bf16x8*)(p.sg + ro + 8);
;       bf16x8 y0, y1;
; #pragma unroll
;       for (int et = 0; et < 8; ++et) {
;         y0[et] = (short)f2bf(bf2f((u16)s0[et]) * ((o[et][j] - mu) * rsd * gv[et]));
;         y1[et] = (short)f2bf(bf2f((u16)s1[et]) * ((o[et + 8][j] - mu) * rsd * gv[et + 8]));
;       }
;       *(bf16x8*)(p.y + ro) = y0; *(bf16x8*)(p.y + ro + 8) = y1;
;     }
	v_add_f32_e32 v18, v38, v42
	v_mul_f32_e32 v18, 0x3b800000, v18
	v_pk_add_f32 v[82:83], v[90:91], v[18:19] op_sel_hi:[1,0] neg_lo:[0,1] neg_hi:[0,1]
	v_mov_b32_e32 v78, v87
	v_mov_b32_e32 v86, v83
	v_mov_b32_e32 v87, v105
	v_pk_add_f32 v[78:79], v[78:79], v[18:19] op_sel_hi:[1,0] neg_lo:[0,1] neg_hi:[0,1]
	v_mov_b32_e32 v62, v71
	v_mov_b32_e32 v70, v82
	v_mov_b32_e32 v71, v104
	v_pk_mul_f32 v[86:87], v[86:87], v[86:87]
	v_pk_add_f32 v[62:63], v[62:63], v[18:19] op_sel_hi:[1,0] neg_lo:[0,1] neg_hi:[0,1]
	v_pk_fma_f32 v[70:71], v[70:71], v[70:71], v[86:87]
	v_mov_b32_e32 v86, v78
	v_mov_b32_e32 v87, v116
	v_mov_b32_e32 v90, v79
	v_mov_b32_e32 v91, v117
	v_pk_fma_f32 v[70:71], v[86:87], v[86:87], v[70:71]
	v_mov_b32_e32 v46, v55
	v_pk_fma_f32 v[70:71], v[90:91], v[90:91], v[70:71]
	v_mov_b32_e32 v86, v62
	v_mov_b32_e32 v87, v118
	v_pk_add_f32 v[46:47], v[46:47], v[18:19] op_sel_hi:[1,0] neg_lo:[0,1] neg_hi:[0,1]
	v_mov_b32_e32 v90, v63
	v_mov_b32_e32 v91, v119
	v_pk_fma_f32 v[70:71], v[86:87], v[86:87], v[70:71]
	v_mov_b32_e32 v86, v46
	v_pk_fma_f32 v[70:71], v[90:91], v[90:91], v[70:71]
	v_mov_b32_e32 v87, v120
	v_pk_add_f32 v[74:75], v[74:75], v[18:19] op_sel_hi:[1,0] neg_lo:[0,1] neg_hi:[0,1]
	v_mov_b32_e32 v42, v51
	v_mov_b32_e32 v34, v39
	v_mov_b32_e32 v90, v47
	v_mov_b32_e32 v91, v121
	v_pk_fma_f32 v[70:71], v[86:87], v[86:87], v[70:71]
	v_pk_add_f32 v[58:59], v[58:59], v[18:19] op_sel_hi:[1,0] neg_lo:[0,1] neg_hi:[0,1]
	v_pk_add_f32 v[42:43], v[42:43], v[18:19] op_sel_hi:[1,0] neg_lo:[0,1] neg_hi:[0,1]
	v_pk_add_f32 v[34:35], v[34:35], v[18:19] op_sel_hi:[1,0] neg_lo:[0,1] neg_hi:[0,1]
	v_mov_b32_e32 v18, v74
	v_mov_b32_e32 v19, v30
	v_pk_fma_f32 v[70:71], v[90:91], v[90:91], v[70:71]
	v_pk_mul_f32 v[66:67], v[58:59], v[58:59]
	v_mov_b32_e32 v54, v75
	v_mov_b32_e32 v55, v31
	v_pk_fma_f32 v[18:19], v[18:19], v[18:19], v[70:71]
	v_pk_mul_f32 v[108:109], v[100:101], v[100:101]
	v_pk_fma_f32 v[18:19], v[54:55], v[54:55], v[18:19]
	v_mov_b32_e32 v54, v66
	v_mov_b32_e32 v55, v106
	v_pk_mul_f32 v[50:51], v[42:43], v[42:43]
	v_pk_add_f32 v[18:19], v[54:55], v[18:19]
	v_mov_b32_e32 v106, v67
	v_pk_add_f32 v[18:19], v[106:107], v[18:19]
	v_mov_b32_e32 v54, v50
	v_mov_b32_e32 v55, v108
	v_pk_mul_f32 v[110:111], v[102:103], v[102:103]
	v_pk_mul_f32 v[38:39], v[34:35], v[34:35]
	v_pk_add_f32 v[18:19], v[54:55], v[18:19]
	v_mov_b32_e32 v108, v51
	v_pk_add_f32 v[18:19], v[108:109], v[18:19]
	v_mov_b32_e32 v50, v38
	v_mov_b32_e32 v51, v110
	v_pk_add_f32 v[18:19], v[50:51], v[18:19]
	v_mov_b32_e32 v110, v39
	v_pk_add_f32 v[18:19], v[110:111], v[18:19]
	ds_bpermute_b32 v39, v99, v19
	ds_bpermute_b32 v38, v99, v18
	s_waitcnt vmcnt(0)
	v_and_b32_e32 v55, 0xffff0000, v26
	v_lshlrev_b32_e32 v54, 16, v26
	v_and_b32_e32 v67, 0xffff0000, v27
	v_lshlrev_b32_e32 v66, 16, v27
	s_waitcnt lgkmcnt(0)
	v_pk_add_f32 v[18:19], v[18:19], v[38:39]
	ds_bpermute_b32 v39, v94, v19
	ds_bpermute_b32 v38, v94, v18
	v_and_b32_e32 v51, 0xffff0000, v20
	v_lshlrev_b32_e32 v50, 16, v20
	v_lshl_add_u64 v[90:91], s[14:15], 0, v[24:25]
	v_or_b32_e32 v24, 1, v22
	s_waitcnt lgkmcnt(0)
	v_pk_add_f32 v[18:19], v[18:19], v[38:39]
	ds_bpermute_b32 v27, v23, v19
	ds_bpermute_b32 v26, v23, v18
	v_and_b32_e32 v39, 0xffff0000, v21
	v_lshlrev_b32_e32 v38, 16, v21
	v_ashrrev_i32_e32 v25, 31, v24
	s_mov_b32 s16, 0x3727c5ac
	s_waitcnt lgkmcnt(0)
	v_pk_add_f32 v[18:19], v[18:19], v[26:27]
	ds_bpermute_b32 v21, v0, v19
	ds_bpermute_b32 v20, v0, v18
	v_lshlrev_b64 v[26:27], 10, v[24:25]
	v_mov_b64_e32 v[24:25], s[16:17]
	v_or3_b32 v26, v26, v98, s96
	v_lshlrev_b64 v[108:109], 1, v[26:27]
	s_waitcnt lgkmcnt(0)
	v_pk_add_f32 v[18:19], v[18:19], v[20:21]
	v_and_b32_e32 v71, 0xffff0000, v28
	v_pk_fma_f32 v[106:107], v[18:19], s[38:39], v[24:25] op_sel_hi:[1,0,0]
	v_lshlrev_b32_e32 v70, 16, v28
	v_mul_f32_e32 v18, 0x4b800000, v107
	v_cmp_gt_f32_e32 vcc, s35, v107
	v_and_b32_e32 v87, 0xffff0000, v29
	v_lshlrev_b32_e32 v86, 16, v29
	v_cndmask_b32_e32 v18, v107, v18, vcc
	v_rsq_f32_e32 v18, v18
	v_lshl_add_u64 v[110:111], s[6:7], 0, v[108:109]
	s_add_i32 s26, s26, s33
	s_cmp_ge_i32 s26, s22
	v_mul_f32_e32 v19, 0x45800000, v18
	v_cndmask_b32_e32 v122, v18, v19, vcc
	v_pk_mul_f32 v[20:21], v[30:31], v[122:123] op_sel_hi:[1,0]
	v_pk_mul_f32 v[18:19], v[104:105], v[122:123] op_sel_hi:[1,0]
	v_pk_mul_f32 v[20:21], v[6:7], v[20:21]
	v_pk_mul_f32 v[18:19], v[14:15], v[18:19]
	v_pk_mul_f32 v[20:21], v[20:21], v[112:113]
	v_pk_mul_f32 v[18:19], v[18:19], v[54:55]
	v_cvt_pk_bf16_f32 v26, v20, v21
	v_pk_mul_f32 v[20:21], v[116:117], v[122:123] op_sel_hi:[1,0]
	v_cvt_pk_bf16_f32 v18, v18, v19
	v_pk_mul_f32 v[20:21], v[16:17], v[20:21]
	v_pk_mul_f32 v[30:31], v[120:121], v[122:123] op_sel_hi:[1,0]
	v_pk_mul_f32 v[20:21], v[20:21], v[66:67]
	v_pk_mul_f32 v[30:31], v[12:13], v[30:31]
	v_cvt_pk_bf16_f32 v19, v20, v21
	v_pk_mul_f32 v[20:21], v[32:33], v[122:123] op_sel_hi:[1,0]
	v_pk_mul_f32 v[30:31], v[30:31], v[86:87]
	v_pk_mul_f32 v[20:21], v[8:9], v[20:21]
	v_pk_mul_f32 v[28:29], v[100:101], v[122:123] op_sel_hi:[1,0]
	v_pk_mul_f32 v[20:21], v[20:21], v[114:115]
	v_pk_mul_f32 v[28:29], v[2:3], v[28:29]
	v_cvt_pk_bf16_f32 v27, v20, v21
	v_pk_mul_f32 v[20:21], v[118:119], v[122:123] op_sel_hi:[1,0]
	v_pk_mul_f32 v[28:29], v[28:29], v[50:51]
	v_pk_mul_f32 v[20:21], v[10:11], v[20:21]
	v_cvt_pk_bf16_f32 v28, v28, v29
	v_pk_mul_f32 v[20:21], v[20:21], v[70:71]
	v_cmp_gt_f32_e32 vcc, s35, v106
	v_cvt_pk_bf16_f32 v20, v20, v21
	v_cvt_pk_bf16_f32 v21, v30, v31
	v_pk_mul_f32 v[30:31], v[102:103], v[122:123] op_sel_hi:[1,0]
	s_nop 0
	v_pk_mul_f32 v[30:31], v[4:5], v[30:31]
	s_nop 0
	v_pk_mul_f32 v[30:31], v[30:31], v[38:39]
; DEVINL float bf2f(u16 h) { return __uint_as_float(((unsigned)h) << 16); }
; DEVINL void ret_out_phase(CParams& p, const Ctx& cx, int l, const GI& gi) {
;     ...
; #pragma unroll
;     for (int j = 0; j < 4; ++j) {
;       float sm = 0.f;
; #pragma unroll
;       for (int et = 0; et < 16; ++et) sm += o[et][j];
; #pragma unroll
;       for (int x = 1; x < 16; x <<= 1) sm += shflx(sm, x, lane);
;       const float mu = sm * (1.f / 256.f);
;       float vs = 0.f;
; #pragma unroll
;       for (int et = 0; et < 16; ++et) { const float d = o[et][j] - mu; vs += d * d; }
; #pragma unroll
;       for (int x = 1; x < 16; x <<= 1) vs += shflx(vs, x, lane);
;       const float rsd = rsqrtf(vs * (1.f / 256.f) + 1e-5f);
;       const size_t ro = (size_t)(row0 + wave * 16 + fq * 4 + j) * DM + h * 256 + fr * 16;
;       const bf16x8 s0 = *(const bf16x8*)(p.sg + ro), s1 = *(const bf16x8*)(p.sg + ro + 8);
;       bf16x8 y0, y1;
; #pragma unroll
;       for (int et = 0; et < 8; ++et) {
;         y0[et] = (short)f2bf(bf2f((u16)s0[et]) * ((o[et][j] - mu) * rsd * gv[et]));
;         y1[et] = (short)f2bf(bf2f((u16)s1[et]) * ((o[et + 8][j] - mu) * rsd * gv[et + 8]));
;       }
;       *(bf16x8*)(p.y + ro) = y0; *(bf16x8*)(p.y + ro + 8) = y1;
;     }
	s_nop 0
	v_cvt_pk_bf16_f32 v29, v30, v31
	global_store_dwordx4 v[90:91], v[18:21], off
	global_store_dwordx4 v[90:91], v[26:29], off offset:16
	s_nop 1
	v_mov_b32_e32 v18, v172
	v_mov_b32_e32 v19, v173
	v_mov_b32_e32 v20, v174
	v_mov_b32_e32 v21, v175
	v_mov_b32_e32 v26, v176
	v_mov_b32_e32 v27, v177
	v_mov_b32_e32 v28, v178
	v_mov_b32_e32 v29, v179
	v_and_b32_e32 v39, 0xffff0000, v20
	v_lshlrev_b32_e32 v38, 16, v20
	v_mul_f32_e32 v20, 0x4b800000, v106
	v_cndmask_b32_e32 v20, v106, v20, vcc
	v_rsq_f32_e32 v20, v20
	v_and_b32_e32 v67, 0xffff0000, v21
	v_lshlrev_b32_e32 v66, 16, v21
	v_and_b32_e32 v31, 0xffff0000, v18
	v_mul_f32_e32 v21, 0x45800000, v20
	v_cndmask_b32_e32 v86, v20, v21, vcc
	v_pk_mul_f32 v[20:21], v[82:83], v[86:87] op_sel_hi:[1,0]
	v_lshlrev_b32_e32 v30, 16, v18
	v_and_b32_e32 v33, 0xffff0000, v19
	v_lshlrev_b32_e32 v32, 16, v19
	v_and_b32_e32 v19, 0xffff0000, v26
	v_lshlrev_b32_e32 v18, 16, v26
	v_pk_mul_f32 v[20:21], v[14:15], v[20:21]
	v_and_b32_e32 v51, 0xffff0000, v27
	v_pk_mul_f32 v[18:19], v[20:21], v[18:19]
	v_pk_mul_f32 v[20:21], v[74:75], v[86:87] op_sel_hi:[1,0]
	v_lshlrev_b32_e32 v50, 16, v27
	v_pk_mul_f32 v[20:21], v[6:7], v[20:21]
	v_cvt_pk_bf16_f32 v18, v18, v19
	v_pk_mul_f32 v[20:21], v[20:21], v[30:31]
	v_pk_mul_f32 v[30:31], v[46:47], v[86:87] op_sel_hi:[1,0]
	v_cvt_pk_bf16_f32 v26, v20, v21
	v_pk_mul_f32 v[20:21], v[78:79], v[86:87] op_sel_hi:[1,0]
	v_and_b32_e32 v55, 0xffff0000, v28
	v_pk_mul_f32 v[20:21], v[16:17], v[20:21]
	v_lshlrev_b32_e32 v54, 16, v28
	v_pk_mul_f32 v[20:21], v[20:21], v[50:51]
	v_and_b32_e32 v71, 0xffff0000, v29
	v_cvt_pk_bf16_f32 v19, v20, v21
	v_pk_mul_f32 v[20:21], v[58:59], v[86:87] op_sel_hi:[1,0]
	v_lshlrev_b32_e32 v70, 16, v29
	v_pk_mul_f32 v[20:21], v[8:9], v[20:21]
	v_pk_mul_f32 v[30:31], v[12:13], v[30:31]
	v_pk_mul_f32 v[20:21], v[20:21], v[32:33]
	v_pk_mul_f32 v[30:31], v[30:31], v[70:71]
	v_cvt_pk_bf16_f32 v27, v20, v21
	v_pk_mul_f32 v[20:21], v[62:63], v[86:87] op_sel_hi:[1,0]
	v_pk_mul_f32 v[28:29], v[42:43], v[86:87] op_sel_hi:[1,0]
	v_pk_mul_f32 v[20:21], v[10:11], v[20:21]
	v_pk_mul_f32 v[28:29], v[2:3], v[28:29]
	v_pk_mul_f32 v[20:21], v[20:21], v[54:55]
	v_pk_mul_f32 v[28:29], v[28:29], v[38:39]
	v_cvt_pk_bf16_f32 v20, v20, v21
	v_cvt_pk_bf16_f32 v21, v30, v31
	v_pk_mul_f32 v[30:31], v[34:35], v[86:87] op_sel_hi:[1,0]
	v_cvt_pk_bf16_f32 v28, v28, v29
	v_pk_mul_f32 v[30:31], v[4:5], v[30:31]
	v_mov_b32_e32 v32, v68
	v_pk_mul_f32 v[30:31], v[30:31], v[66:67]
	v_mov_b32_e32 v33, v60
	v_cvt_pk_bf16_f32 v29, v30, v31
	v_lshl_add_u64 v[30:31], s[14:15], 0, v[108:109]
	global_store_dwordx4 v[30:31], v[18:21], off
	global_store_dwordx4 v[30:31], v[26:29], off offset:16
	v_add_f32_e32 v30, 0, v96
	v_or_b32_e32 v18, 2, v22
	v_ashrrev_i32_e32 v19, 31, v18
	v_lshlrev_b64 v[18:19], 10, v[18:19]
	v_or3_b32 v18, v18, v98, s96
	v_lshlrev_b64 v[26:27], 1, v[18:19]
	v_lshl_add_u64 v[28:29], s[6:7], 0, v[26:27]
	s_nop 1
	v_mov_b32_e32 v18, v180
	v_mov_b32_e32 v19, v181
	v_mov_b32_e32 v20, v182
	v_mov_b32_e32 v21, v183
	v_mov_b32_e32 v100, v184
	v_mov_b32_e32 v101, v185
	v_mov_b32_e32 v102, v186
	v_mov_b32_e32 v103, v187
	v_add_f32_e32 v30, v30, v92
	v_add_f32_e32 v30, v30, v88
	v_add_f32_e32 v30, v30, v80
	v_add_f32_e32 v30, v30, v72
	v_add_f32_e32 v30, v30, v64
	v_add_f32_e32 v30, v30, v56
	v_add_f32_e32 v30, v30, v48
	v_add_f32_e32 v30, v30, v84
	v_add_f32_e32 v30, v30, v76
	v_add_f32_e32 v30, v30, v68
	v_add_f32_e32 v30, v30, v60
	v_add_f32_e32 v30, v30, v52
	v_add_f32_e32 v30, v30, v44
	v_add_f32_e32 v30, v30, v40
	v_add_f32_e32 v30, v30, v36
	ds_bpermute_b32 v31, v99, v30
	v_mov_b32_e32 v29, v76
	v_mov_b32_e32 v50, v40
	v_mov_b32_e32 v51, v36
	v_mov_b32_e32 v58, v96
	s_waitcnt lgkmcnt(0)
	v_add_f32_e32 v30, v30, v31
	ds_bpermute_b32 v31, v94, v30
	v_mov_b32_e32 v59, v92
	v_mov_b32_e32 v62, v88
	v_mov_b32_e32 v63, v80
	v_mov_b32_e32 v66, v72
	s_waitcnt lgkmcnt(0)
	v_add_f32_e32 v30, v30, v31
	ds_bpermute_b32 v31, v23, v30
	v_mov_b32_e32 v67, v64
	v_mov_b32_e32 v70, v56
	v_mov_b32_e32 v71, v48
	v_mov_b32_e32 v76, v85
	s_waitcnt lgkmcnt(0)
	v_add_f32_e32 v30, v30, v31
	ds_bpermute_b32 v31, v0, v30
	v_mov_b32_e32 v92, v97
	v_mov_b32_e32 v80, v89
	v_mov_b32_e32 v64, v73
	v_mov_b32_e32 v60, v69
	s_waitcnt lgkmcnt(0)
	v_add_f32_e32 v28, v30, v31
	v_mul_f32_e32 v38, 0x3b800000, v28
	v_mov_b32_e32 v28, v84
	v_pk_add_f32 v[30:31], v[28:29], v[38:39] op_sel_hi:[1,0] neg_lo:[0,1] neg_hi:[0,1]
	v_pk_add_f32 v[32:33], v[32:33], v[38:39] op_sel_hi:[1,0] neg_lo:[0,1] neg_hi:[0,1]
	v_mov_b32_e32 v48, v57
	v_pk_mul_f32 v[42:43], v[32:33], v[32:33]
	v_or_b32_e32 v22, 3, v22
	v_and_b32_e32 v29, 0xffff0000, v18
	v_lshlrev_b32_e32 v28, 16, v18
	v_and_b32_e32 v35, 0xffff0000, v19
	v_lshlrev_b32_e32 v34, 16, v19
	v_mov_b32_e32 v18, v52
	v_mov_b32_e32 v19, v44
	v_pk_add_f32 v[18:19], v[18:19], v[38:39] op_sel_hi:[1,0] neg_lo:[0,1] neg_hi:[0,1]
	v_add_f32_e32 v39, 0, v97
	v_add_f32_e32 v39, v39, v93
	v_add_f32_e32 v39, v39, v89
	v_add_f32_e32 v39, v39, v81
	v_add_f32_e32 v39, v39, v73
	v_add_f32_e32 v39, v39, v65
	v_add_f32_e32 v39, v39, v57
	v_add_f32_e32 v39, v39, v49
	v_add_f32_e32 v39, v39, v85
	v_add_f32_e32 v39, v39, v77
	v_add_f32_e32 v39, v39, v69
	v_add_f32_e32 v39, v39, v61
	v_add_f32_e32 v39, v39, v53
	v_add_f32_e32 v39, v39, v45
	v_add_f32_e32 v39, v39, v41
	v_add_f32_e32 v39, v39, v37
	ds_bpermute_b32 v44, v99, v39
	v_pk_add_f32 v[50:51], v[50:51], v[38:39] op_sel_hi:[1,0] neg_lo:[0,1] neg_hi:[0,1]
	v_mov_b32_e32 v57, v31
	v_pk_mul_f32 v[46:47], v[18:19], v[18:19]
	v_pk_mul_f32 v[54:55], v[50:51], v[50:51]
	s_waitcnt lgkmcnt(0)
	v_add_f32_e32 v36, v39, v44
	ds_bpermute_b32 v39, v94, v36
	v_mov_b32_e32 v44, v53
	s_waitcnt lgkmcnt(0)
; DEVINL float bf2f(u16 h) { return __uint_as_float(((unsigned)h) << 16); }
; DEVINL void ret_out_phase(CParams& p, const Ctx& cx, int l, const GI& gi) {
;     ...
; #pragma unroll
;     for (int j = 0; j < 4; ++j) {
;       float sm = 0.f;
; #pragma unroll
;       for (int et = 0; et < 16; ++et) sm += o[et][j];
; #pragma unroll
;       for (int x = 1; x < 16; x <<= 1) sm += shflx(sm, x, lane);
;       const float mu = sm * (1.f / 256.f);
;       float vs = 0.f;
; #pragma unroll
;       for (int et = 0; et < 16; ++et) { const float d = o[et][j] - mu; vs += d * d; }
; #pragma unroll
;       for (int x = 1; x < 16; x <<= 1) vs += shflx(vs, x, lane);
;       const float rsd = rsqrtf(vs * (1.f / 256.f) + 1e-5f);
;       const size_t ro = (size_t)(row0 + wave * 16 + fq * 4 + j) * DM + h * 256 + fr * 16;
;       const bf16x8 s0 = *(const bf16x8*)(p.sg + ro), s1 = *(const bf16x8*)(p.sg + ro + 8);
;       bf16x8 y0, y1;
; #pragma unroll
;       for (int et = 0; et < 8; ++et) {
;         y0[et] = (short)f2bf(bf2f((u16)s0[et]) * ((o[et][j] - mu) * rsd * gv[et]));
;         y1[et] = (short)f2bf(bf2f((u16)s1[et]) * ((o[et + 8][j] - mu) * rsd * gv[et + 8]));
;       }
;       *(bf16x8*)(p.y + ro) = y0; *(bf16x8*)(p.y + ro + 8) = y1;
;     }
	v_add_f32_e32 v36, v36, v39
	v_pk_add_f32 v[58:59], v[58:59], v[38:39] op_sel_hi:[1,0] neg_lo:[0,1] neg_hi:[0,1]
	ds_bpermute_b32 v39, v23, v36
	v_mov_b32_e32 v73, v58
	s_waitcnt lgkmcnt(0)
	v_add_f32_e32 v36, v36, v39
	ds_bpermute_b32 v40, v0, v36
	v_pk_add_f32 v[62:63], v[62:63], v[38:39] op_sel_hi:[1,0] neg_lo:[0,1] neg_hi:[0,1]
	v_pk_add_f32 v[66:67], v[66:67], v[38:39] op_sel_hi:[1,0] neg_lo:[0,1] neg_hi:[0,1]
	v_pk_add_f32 v[38:39], v[70:71], v[38:39] op_sel_hi:[1,0] neg_lo:[0,1] neg_hi:[0,1]
	v_mov_b32_e32 v83, v63
	s_waitcnt lgkmcnt(0)
	v_add_f32_e32 v36, v36, v40
	v_mul_f32_e32 v40, 0x3b800000, v36
	v_pk_add_f32 v[70:71], v[76:77], v[40:41] op_sel_hi:[1,0] neg_lo:[0,1] neg_hi:[0,1]
	v_pk_add_f32 v[76:77], v[92:93], v[40:41] op_sel_hi:[1,0] neg_lo:[0,1] neg_hi:[0,1]
	v_pk_add_f32 v[78:79], v[80:81], v[40:41] op_sel_hi:[1,0] neg_lo:[0,1] neg_hi:[0,1]
	v_mov_b32_e32 v80, v77
	v_mov_b32_e32 v81, v59
	v_mov_b32_e32 v72, v76
	v_pk_mul_f32 v[80:81], v[80:81], v[80:81]
	v_pk_add_f32 v[64:65], v[64:65], v[40:41] op_sel_hi:[1,0] neg_lo:[0,1] neg_hi:[0,1]
	v_pk_fma_f32 v[72:73], v[72:73], v[72:73], v[80:81]
	v_mov_b32_e32 v80, v78
	v_mov_b32_e32 v81, v62
	v_mov_b32_e32 v82, v79
	v_pk_fma_f32 v[72:73], v[80:81], v[80:81], v[72:73]
	v_mov_b32_e32 v36, v41
	v_pk_fma_f32 v[72:73], v[82:83], v[82:83], v[72:73]
	v_mov_b32_e32 v80, v64
	v_mov_b32_e32 v81, v66
	v_pk_add_f32 v[60:61], v[60:61], v[40:41] op_sel_hi:[1,0] neg_lo:[0,1] neg_hi:[0,1]
	v_pk_add_f32 v[44:45], v[44:45], v[40:41] op_sel_hi:[1,0] neg_lo:[0,1] neg_hi:[0,1]
	v_pk_add_f32 v[36:37], v[36:37], v[40:41] op_sel_hi:[1,0] neg_lo:[0,1] neg_hi:[0,1]
	v_pk_add_f32 v[40:41], v[48:49], v[40:41] op_sel_hi:[1,0] neg_lo:[0,1] neg_hi:[0,1]
	v_mov_b32_e32 v82, v65
	v_mov_b32_e32 v83, v67
	v_pk_fma_f32 v[72:73], v[80:81], v[80:81], v[72:73]
	v_mov_b32_e32 v80, v40
	v_pk_fma_f32 v[72:73], v[82:83], v[82:83], v[72:73]
	v_mov_b32_e32 v81, v38
	v_mov_b32_e32 v82, v41
	v_mov_b32_e32 v83, v39
	v_pk_fma_f32 v[72:73], v[80:81], v[80:81], v[72:73]
	v_mov_b32_e32 v48, v70
	v_mov_b32_e32 v49, v30
	v_pk_fma_f32 v[72:73], v[82:83], v[82:83], v[72:73]
	v_pk_mul_f32 v[68:69], v[60:61], v[60:61]
	v_mov_b32_e32 v56, v71
	v_pk_fma_f32 v[48:49], v[48:49], v[48:49], v[72:73]
	v_pk_mul_f32 v[52:53], v[44:45], v[44:45]
	v_pk_fma_f32 v[48:49], v[56:57], v[56:57], v[48:49]
	v_mov_b32_e32 v56, v68
	v_mov_b32_e32 v57, v42
	v_pk_add_f32 v[48:49], v[56:57], v[48:49]
	v_mov_b32_e32 v42, v69
	v_pk_add_f32 v[42:43], v[42:43], v[48:49]
	v_mov_b32_e32 v48, v52
	v_mov_b32_e32 v49, v46
	v_pk_mul_f32 v[74:75], v[36:37], v[36:37]
	v_pk_add_f32 v[42:43], v[48:49], v[42:43]
	v_mov_b32_e32 v46, v53
	v_pk_add_f32 v[42:43], v[46:47], v[42:43]
	v_mov_b32_e32 v46, v74
	v_mov_b32_e32 v47, v54
	v_pk_add_f32 v[42:43], v[46:47], v[42:43]
	v_mov_b32_e32 v54, v75
	v_pk_add_f32 v[42:43], v[54:55], v[42:43]
	ds_bpermute_b32 v47, v99, v43
	ds_bpermute_b32 v46, v99, v42
	v_and_b32_e32 v49, 0xffff0000, v20
	v_lshlrev_b32_e32 v48, 16, v20
	v_and_b32_e32 v69, 0xffff0000, v21
	v_lshlrev_b32_e32 v68, 16, v21
	s_waitcnt lgkmcnt(0)
	v_pk_add_f32 v[42:43], v[42:43], v[46:47]
	ds_bpermute_b32 v47, v94, v43
	ds_bpermute_b32 v46, v94, v42
	v_and_b32_e32 v53, 0xffff0000, v100
	v_lshlrev_b32_e32 v52, 16, v100
	v_and_b32_e32 v55, 0xffff0000, v101
	v_lshlrev_b32_e32 v54, 16, v101
	s_waitcnt lgkmcnt(0)
	v_pk_add_f32 v[42:43], v[42:43], v[46:47]
	ds_bpermute_b32 v47, v23, v43
	ds_bpermute_b32 v46, v23, v42
	v_ashrrev_i32_e32 v23, 31, v22
	v_lshlrev_b64 v[22:23], 10, v[22:23]
	v_or3_b32 v22, v22, v98, s96
	v_lshlrev_b64 v[74:75], 1, v[22:23]
	s_waitcnt lgkmcnt(0)
	v_pk_add_f32 v[20:21], v[42:43], v[46:47]
	ds_bpermute_b32 v43, v0, v21
	ds_bpermute_b32 v42, v0, v20
	v_lshl_add_u64 v[46:47], s[14:15], 0, v[26:27]
	v_and_b32_e32 v57, 0xffff0000, v102
	v_lshlrev_b32_e32 v56, 16, v102
	v_and_b32_e32 v73, 0xffff0000, v103
	s_waitcnt lgkmcnt(0)
; DEVINL float bf2f(u16 h) { return __uint_as_float(((unsigned)h) << 16); }
; DEVINL void ret_out_phase(CParams& p, const Ctx& cx, int l, const GI& gi) {
;     ...
; #pragma unroll
;     for (int j = 0; j < 4; ++j) {
;       float sm = 0.f;
; #pragma unroll
;       for (int et = 0; et < 16; ++et) sm += o[et][j];
; #pragma unroll
;       for (int x = 1; x < 16; x <<= 1) sm += shflx(sm, x, lane);
;       const float mu = sm * (1.f / 256.f);
;       float vs = 0.f;
; #pragma unroll
;       for (int et = 0; et < 16; ++et) { const float d = o[et][j] - mu; vs += d * d; }
; #pragma unroll
;       for (int x = 1; x < 16; x <<= 1) vs += shflx(vs, x, lane);
;       const float rsd = rsqrtf(vs * (1.f / 256.f) + 1e-5f);
;       const size_t ro = (size_t)(row0 + wave * 16 + fq * 4 + j) * DM + h * 256 + fr * 16;
;       const bf16x8 s0 = *(const bf16x8*)(p.sg + ro), s1 = *(const bf16x8*)(p.sg + ro + 8);
;       bf16x8 y0, y1;
; #pragma unroll
;       for (int et = 0; et < 8; ++et) {
;         y0[et] = (short)f2bf(bf2f((u16)s0[et]) * ((o[et][j] - mu) * rsd * gv[et]));
;         y1[et] = (short)f2bf(bf2f((u16)s1[et]) * ((o[et + 8][j] - mu) * rsd * gv[et + 8]));
;       }
;       *(bf16x8*)(p.y + ro) = y0; *(bf16x8*)(p.y + ro + 8) = y1;
;     }
	v_pk_add_f32 v[20:21], v[20:21], v[42:43]
	v_lshlrev_b32_e32 v72, 16, v103
	v_pk_fma_f32 v[42:43], v[20:21], s[38:39], v[24:25] op_sel_hi:[1,0,0]
	v_lshl_add_u64 v[80:81], s[6:7], 0, v[74:75]
	v_mul_f32_e32 v0, 0x4b800000, v43
	v_cmp_gt_f32_e32 vcc, s35, v43
	s_nop 1
	v_cndmask_b32_e32 v0, v43, v0, vcc
	v_rsq_f32_e32 v0, v0
	s_nop 0
	v_mul_f32_e32 v20, 0x45800000, v0
	v_cndmask_b32_e32 v0, v0, v20, vcc
	v_pk_mul_f32 v[22:23], v[30:31], v[0:1] op_sel_hi:[1,0]
	v_pk_mul_f32 v[20:21], v[58:59], v[0:1] op_sel_hi:[1,0]
	v_pk_mul_f32 v[22:23], v[6:7], v[22:23]
	v_pk_mul_f32 v[20:21], v[14:15], v[20:21]
	v_pk_mul_f32 v[22:23], v[22:23], v[28:29]
	v_pk_mul_f32 v[20:21], v[20:21], v[52:53]
	v_cvt_pk_bf16_f32 v24, v22, v23
	v_pk_mul_f32 v[22:23], v[62:63], v[0:1] op_sel_hi:[1,0]
	v_cvt_pk_bf16_f32 v20, v20, v21
	v_pk_mul_f32 v[22:23], v[16:17], v[22:23]
	v_pk_mul_f32 v[18:19], v[18:19], v[0:1] op_sel_hi:[1,0]
	v_pk_mul_f32 v[22:23], v[22:23], v[54:55]
	v_pk_mul_f32 v[18:19], v[2:3], v[18:19]
	v_cvt_pk_bf16_f32 v21, v22, v23
	v_pk_mul_f32 v[22:23], v[32:33], v[0:1] op_sel_hi:[1,0]
	v_pk_mul_f32 v[18:19], v[18:19], v[48:49]
	v_pk_mul_f32 v[22:23], v[8:9], v[22:23]
	v_cvt_pk_bf16_f32 v26, v18, v19
	v_pk_mul_f32 v[22:23], v[22:23], v[34:35]
	v_pk_mul_f32 v[18:19], v[38:39], v[0:1] op_sel_hi:[1,0]
	v_cvt_pk_bf16_f32 v25, v22, v23
	v_pk_mul_f32 v[22:23], v[66:67], v[0:1] op_sel_hi:[1,0]
	v_pk_mul_f32 v[18:19], v[12:13], v[18:19]
	v_pk_mul_f32 v[22:23], v[10:11], v[22:23]
	v_pk_mul_f32 v[18:19], v[18:19], v[72:73]
	v_pk_mul_f32 v[22:23], v[22:23], v[56:57]
	v_cmp_gt_f32_e32 vcc, s35, v42
	v_cvt_pk_bf16_f32 v22, v22, v23
	v_cvt_pk_bf16_f32 v23, v18, v19
	v_pk_mul_f32 v[18:19], v[50:51], v[0:1] op_sel_hi:[1,0]
	v_mul_f32_e32 v0, 0x4b800000, v42
	v_pk_mul_f32 v[18:19], v[4:5], v[18:19]
	v_cndmask_b32_e32 v0, v42, v0, vcc
	v_pk_mul_f32 v[18:19], v[18:19], v[68:69]
	v_rsq_f32_e32 v0, v0
	v_cvt_pk_bf16_f32 v27, v18, v19
	global_store_dwordx4 v[46:47], v[20:23], off
	global_store_dwordx4 v[46:47], v[24:27], off offset:16
	s_nop 1
	v_mov_b32_e32 v18, v188
	v_mov_b32_e32 v19, v189
	v_mov_b32_e32 v20, v190
	v_mov_b32_e32 v21, v191
	v_mov_b32_e32 v22, v192
	v_mov_b32_e32 v23, v193
	v_mov_b32_e32 v24, v194
	v_mov_b32_e32 v25, v195
	v_and_b32_e32 v27, 0xffff0000, v18
	v_and_b32_e32 v31, 0xffff0000, v22
	v_lshlrev_b32_e32 v30, 16, v22
	v_and_b32_e32 v33, 0xffff0000, v23
	v_lshlrev_b32_e32 v32, 16, v23
	v_and_b32_e32 v23, 0xffff0000, v24
	v_lshlrev_b32_e32 v22, 16, v24
	v_mul_f32_e32 v24, 0x45800000, v0
	v_cndmask_b32_e32 v0, v0, v24, vcc
	v_lshlrev_b32_e32 v26, 16, v18
	v_and_b32_e32 v29, 0xffff0000, v19
	v_lshlrev_b32_e32 v28, 16, v19
	v_and_b32_e32 v19, 0xffff0000, v20
	v_lshlrev_b32_e32 v18, 16, v20
	v_and_b32_e32 v35, 0xffff0000, v21
	v_lshlrev_b32_e32 v34, 16, v21
	v_and_b32_e32 v21, 0xffff0000, v25
	v_lshlrev_b32_e32 v20, 16, v25
	v_pk_mul_f32 v[24:25], v[76:77], v[0:1] op_sel_hi:[1,0]
	s_nop 0
	v_pk_mul_f32 v[14:15], v[14:15], v[24:25]
	v_pk_mul_f32 v[24:25], v[70:71], v[0:1] op_sel_hi:[1,0]
	v_pk_mul_f32 v[14:15], v[14:15], v[30:31]
	v_pk_mul_f32 v[6:7], v[6:7], v[24:25]
	v_pk_mul_f32 v[24:25], v[78:79], v[0:1] op_sel_hi:[1,0]
	v_cvt_pk_bf16_f32 v14, v14, v15
	v_pk_mul_f32 v[16:17], v[16:17], v[24:25]
	v_pk_mul_f32 v[6:7], v[6:7], v[26:27]
	v_pk_mul_f32 v[16:17], v[16:17], v[32:33]
	v_cvt_pk_bf16_f32 v6, v6, v7
	v_cvt_pk_bf16_f32 v15, v16, v17
	v_pk_mul_f32 v[16:17], v[60:61], v[0:1] op_sel_hi:[1,0]
	s_nop 0
	v_pk_mul_f32 v[8:9], v[8:9], v[16:17]
	s_nop 0
	v_pk_mul_f32 v[8:9], v[8:9], v[28:29]
	s_nop 0
	v_cvt_pk_bf16_f32 v7, v8, v9
	v_pk_mul_f32 v[8:9], v[64:65], v[0:1] op_sel_hi:[1,0]
	s_nop 0
	v_pk_mul_f32 v[8:9], v[10:11], v[8:9]
	s_nop 0
	v_pk_mul_f32 v[8:9], v[8:9], v[22:23]
	s_nop 0
	v_cvt_pk_bf16_f32 v16, v8, v9
	v_pk_mul_f32 v[8:9], v[44:45], v[0:1] op_sel_hi:[1,0]
	s_nop 0
	v_pk_mul_f32 v[2:3], v[2:3], v[8:9]
	s_nop 0
	v_pk_mul_f32 v[2:3], v[2:3], v[18:19]
	s_nop 0
	v_cvt_pk_bf16_f32 v8, v2, v3
	v_pk_mul_f32 v[2:3], v[40:41], v[0:1] op_sel_hi:[1,0]
	s_nop 0
	v_pk_mul_f32 v[2:3], v[12:13], v[2:3]
	s_nop 0
	v_pk_mul_f32 v[2:3], v[2:3], v[20:21]
	s_nop 0
	v_cvt_pk_bf16_f32 v17, v2, v3
	v_pk_mul_f32 v[2:3], v[36:37], v[0:1] op_sel_hi:[1,0]
	s_nop 0
	v_pk_mul_f32 v[2:3], v[4:5], v[2:3]
	s_nop 0
	v_pk_mul_f32 v[2:3], v[2:3], v[34:35]
	s_nop 0
	v_cvt_pk_bf16_f32 v9, v2, v3
	v_lshl_add_u64 v[2:3], s[14:15], 0, v[74:75]
	global_store_dwordx4 v[2:3], v[14:17], off
	global_store_dwordx4 v[2:3], v[6:9], off offset:16
	s_cbranch_scc1 .LBB0_275
